# P6 K-loop rewritten: 64-MFMA segments, split staging lead/trail 8+8 DMAs, 2 barriers per K-tile (plus P4/P6 epilogue load batching)
# speedup vs baseline: 1.0035x; 1.0035x over previous
.LBB0_840:
	s_lshl_b32 s6, s6, 5
	s_and_b32 s25, s6, 0x60
	s_mov_b64 s[6:7], 0x80
	s_add_i32 m0, s37, 0x18000
	v_lshl_add_u64 v[6:7], v[6:7], 0, s[6:7]
	s_lshl_b32 s24, s17, 13
	s_lshl_b32 s26, s25, 7
	s_waitcnt vmcnt(0)
	s_barrier
	global_load_lds_dwordx4 v[6:7], off
	v_lshl_add_u64 v[4:5], v[4:5], 0, s[6:7]
	s_add_i32 m0, s37, 0x1a000
	s_add_i32 s45, s37, 0x8000
	s_add_i32 s46, s37, 0xa000
	global_load_lds_dwordx4 v[4:5], off
	v_lshl_add_u64 v[0:1], v[0:1], 0, s[6:7]
	s_mov_b32 m0, s45
	s_add_u32 s22, s30, 0x80080
	global_load_lds_dwordx4 v[0:1], off
	v_lshl_add_u64 v[0:1], v[2:3], 0, s[6:7]
	s_mov_b32 m0, s46
	s_addc_u32 s23, s31, 0
	global_load_lds_dwordx4 v[0:1], off
	s_add_u32 s58, s12, 0x80080
	s_addc_u32 s59, s13, 0
	s_add_i32 m0, s37, 0xc000
	s_nop 0
	global_load_lds_dwordx4 v150, s[58:59]
	s_add_i32 m0, s37, 0x1c000
	v_lshl_add_u64 v[0:1], s[22:23], 0, v[148:149]
	global_load_lds_dwordx4 v[0:1], off
	v_lshl_add_u64 v[0:1], s[22:23], 0, v[144:145]
	s_add_i32 m0, s37, 0x1e000
	s_cmpk_lt_u32 s16, 0x100
	global_load_lds_dwordx4 v[0:1], off
	v_lshrrev_b32_e32 v0, 1, v9
	v_and_b32_e32 v0, 24, v0
	v_and_b32_e32 v1, 15, v9
	v_lshlrev_b32_e32 v2, 1, v0
	v_lshl_or_b32 v166, s17, 6, v1
	v_lshl_or_b32 v1, v1, 6, v2
	v_lshlrev_b32_e32 v2, 2, v9
	v_and_b32_e32 v2, 32, v2
	v_bitop3_b32 v3, v1, s24, v2 bitop3:0xde
	v_bitop3_b32 v167, v1, s26, v2 bitop3:0xde
	v_lshlrev_b32_e32 v1, 15, v13
	v_and_b32_e32 v1, 0xffff0000, v1
	v_lshl_add_u32 v1, v12, 12, v1
	v_and_b32_e32 v2, 1, v13
	v_lshl_or_b32 v1, v2, 6, v1
	v_lshl_add_u32 v154, v14, 1, v1
	v_lshlrev_b32_e32 v1, 15, v8
	v_and_b32_e32 v1, 0xffff0000, v1
	s_waitcnt vmcnt(6)
	v_lshl_add_u32 v1, v10, 12, v1
	v_and_b32_e32 v2, 1, v8
	s_cselect_b64 s[16:17], -1, 0
	v_lshl_or_b32 v1, v2, 6, v1
	s_add_i32 s47, 0, 0x10000
	s_add_i32 s48, 0, 0x14000
	s_sext_i32_i16 s11, s0
	v_or_b32_e32 v168, s25, v0
	v_mov_b32_e32 v155, v153
	v_lshl_add_u32 v156, v11, 1, v1
	v_mov_b32_e32 v157, v153
	v_mov_b64_e32 v[158:159], 0x580
	v_mov_b64_e32 v[160:161], 0x57f
	v_add_u32_e32 v169, s47, v167
	v_add_u32_e32 v170, s48, v167
	v_add_u32_e32 v171, 0, v3
	v_mov_b32_e32 v172, 0x358637bd
	s_movk_i32 s49, 0x2c00
	s_lshl_b32 s0, s25, 1
	v_lshlrev_b32_e32 v152, 1, v0
	s_mov_b32 s51, s1
	s_barrier
	s_branch .LBB0_843

.LBB0_846:
	s_add_u32 s30, s12, 0xfff80080
	s_addc_u32 s31, s13, -1
	s_cmp_eq_u32 s56, 28
	s_cselect_b32 s35, s25, s31
	s_cselect_b32 s34, s52, s30
	s_cselect_b32 s31, s23, s55
	s_cselect_b32 s30, s53, s54
	s_and_b64 vcc, exec, s[16:17]
	s_cbranch_vccz .Lk64_trail_p6
	s_sub_u32 vcc_lo, s54, 0x80
	s_subb_u32 vcc_hi, s55, 0
	s_add_u32 s58, vcc_lo, 0x20000
	s_addc_u32 s59, vcc_hi, 0
	s_add_i32 m0, s37, 0x18000
	s_nop 0
	global_load_lds_dwordx4 v148, vcc
	s_add_i32 m0, s37, 0x19000
	s_nop 0
	global_load_lds_dwordx4 v148, s[58:59]
	s_add_i32 m0, s37, 0x1a000
	s_nop 0
	global_load_lds_dwordx4 v144, vcc
	s_add_i32 m0, s37, 0x1b000
	s_nop 0
	global_load_lds_dwordx4 v144, s[58:59]
	s_add_u32 vcc_lo, s54, 0x7ff80
	s_addc_u32 vcc_hi, s55, 0
	s_add_u32 s58, vcc_lo, 0x20000
	s_addc_u32 s59, vcc_hi, 0
	s_add_i32 m0, s37, 0x1c000
	s_nop 0
	global_load_lds_dwordx4 v148, vcc
	s_add_i32 m0, s37, 0x1d000
	s_nop 0
	global_load_lds_dwordx4 v148, s[58:59]
	s_add_i32 m0, s37, 0x1e000
	s_nop 0
	global_load_lds_dwordx4 v144, vcc
	s_add_i32 m0, s37, 0x1f000
	s_nop 0
	global_load_lds_dwordx4 v144, s[58:59]
	ds_read_b128 v[32:35], v169 offset:0
	ds_read_b128 v[36:39], v169 offset:1024
	ds_read_b128 v[40:43], v169 offset:2048
	ds_read_b128 v[44:47], v169 offset:3072
	ds_read_b128 v[162:165], v170 offset:0
	ds_read_b128 v[174:177], v170 offset:1024
	ds_read_b128 v[178:181], v170 offset:2048
	ds_read_b128 v[182:185], v170 offset:3072
	ds_read_b128 v[186:189], v171 offset:0
	ds_read_b128 v[190:193], v171 offset:1024
	ds_read_b128 v[194:197], v171 offset:2048
	ds_read_b128 v[198:201], v171 offset:3072
	ds_read_b128 v[202:205], v171 offset:4096
	ds_read_b128 v[206:209], v171 offset:5120
	ds_read_b128 v[210:213], v171 offset:6144
	ds_read_b128 v[214:217], v171 offset:7168
	ds_read_b128 v[220:223], v171 offset:16384
	ds_read_b128 v[224:227], v171 offset:17408
	ds_read_b128 v[228:231], v171 offset:18432
	ds_read_b128 v[232:235], v171 offset:19456
	ds_read_b128 v[236:239], v171 offset:20480
	ds_read_b128 v[240:243], v171 offset:21504
	ds_read_b128 v[244:247], v171 offset:22528
	ds_read_b128 v[248:251], v171 offset:23552
	s_nop 15
	s_nop 15
	s_waitcnt lgkmcnt(0)
	s_barrier
	s_setprio 1
	v_mfma_f32_16x16x32_bf16 v[140:143], v[32:35], v[186:189], v[140:143]
	v_mfma_f32_16x16x32_bf16 v[136:139], v[40:43], v[186:189], v[136:139]
	v_mfma_f32_16x16x32_bf16 v[124:127], v[32:35], v[194:197], v[124:127]
	v_mfma_f32_16x16x32_bf16 v[120:123], v[40:43], v[194:197], v[120:123]
	v_mfma_f32_16x16x32_bf16 v[108:111], v[32:35], v[202:205], v[108:111]
	v_mfma_f32_16x16x32_bf16 v[104:107], v[40:43], v[202:205], v[104:107]
	v_mfma_f32_16x16x32_bf16 v[92:95], v[32:35], v[210:213], v[92:95]
	v_mfma_f32_16x16x32_bf16 v[88:91], v[40:43], v[210:213], v[88:91]
	v_mfma_f32_16x16x32_bf16 v[140:143], v[36:39], v[190:193], v[140:143]
	v_mfma_f32_16x16x32_bf16 v[136:139], v[44:47], v[190:193], v[136:139]
	v_mfma_f32_16x16x32_bf16 v[124:127], v[36:39], v[198:201], v[124:127]
	v_mfma_f32_16x16x32_bf16 v[120:123], v[44:47], v[198:201], v[120:123]
	v_mfma_f32_16x16x32_bf16 v[108:111], v[36:39], v[206:209], v[108:111]
	v_mfma_f32_16x16x32_bf16 v[104:107], v[44:47], v[206:209], v[104:107]
	v_mfma_f32_16x16x32_bf16 v[92:95], v[36:39], v[214:217], v[92:95]
	v_mfma_f32_16x16x32_bf16 v[88:91], v[44:47], v[214:217], v[88:91]
	s_setprio 0
	s_setprio 1
	v_mfma_f32_16x16x32_bf16 v[132:135], v[162:165], v[186:189], v[132:135]
	v_mfma_f32_16x16x32_bf16 v[128:131], v[178:181], v[186:189], v[128:131]
	v_mfma_f32_16x16x32_bf16 v[116:119], v[162:165], v[194:197], v[116:119]
	v_mfma_f32_16x16x32_bf16 v[112:115], v[178:181], v[194:197], v[112:115]
	v_mfma_f32_16x16x32_bf16 v[100:103], v[162:165], v[202:205], v[100:103]
	v_mfma_f32_16x16x32_bf16 v[96:99], v[178:181], v[202:205], v[96:99]
	v_mfma_f32_16x16x32_bf16 v[84:87], v[162:165], v[210:213], v[84:87]
	v_mfma_f32_16x16x32_bf16 v[80:83], v[178:181], v[210:213], v[80:83]
	v_mfma_f32_16x16x32_bf16 v[132:135], v[174:177], v[190:193], v[132:135]
	v_mfma_f32_16x16x32_bf16 v[128:131], v[182:185], v[190:193], v[128:131]
	v_mfma_f32_16x16x32_bf16 v[116:119], v[174:177], v[198:201], v[116:119]
	v_mfma_f32_16x16x32_bf16 v[112:115], v[182:185], v[198:201], v[112:115]
	v_mfma_f32_16x16x32_bf16 v[100:103], v[174:177], v[206:209], v[100:103]
	v_mfma_f32_16x16x32_bf16 v[96:99], v[182:185], v[206:209], v[96:99]
	v_mfma_f32_16x16x32_bf16 v[84:87], v[174:177], v[214:217], v[84:87]
	v_mfma_f32_16x16x32_bf16 v[80:83], v[182:185], v[214:217], v[80:83]
	s_setprio 0
	s_setprio 1
	v_mfma_f32_16x16x32_bf16 v[76:79], v[32:35], v[220:223], v[76:79]
	v_mfma_f32_16x16x32_bf16 v[72:75], v[40:43], v[220:223], v[72:75]
	v_mfma_f32_16x16x32_bf16 v[60:63], v[32:35], v[228:231], v[60:63]
	v_mfma_f32_16x16x32_bf16 v[56:59], v[40:43], v[228:231], v[56:59]
	v_mfma_f32_16x16x32_bf16 v[28:31], v[32:35], v[236:239], v[28:31]
	v_mfma_f32_16x16x32_bf16 v[24:27], v[40:43], v[236:239], v[24:27]
	v_mfma_f32_16x16x32_bf16 v[12:15], v[32:35], v[244:247], v[12:15]
	v_mfma_f32_16x16x32_bf16 v[8:11], v[40:43], v[244:247], v[8:11]
	v_mfma_f32_16x16x32_bf16 v[76:79], v[36:39], v[224:227], v[76:79]
	v_mfma_f32_16x16x32_bf16 v[72:75], v[44:47], v[224:227], v[72:75]
	v_mfma_f32_16x16x32_bf16 v[60:63], v[36:39], v[232:235], v[60:63]
	v_mfma_f32_16x16x32_bf16 v[56:59], v[44:47], v[232:235], v[56:59]
	v_mfma_f32_16x16x32_bf16 v[28:31], v[36:39], v[240:243], v[28:31]
	v_mfma_f32_16x16x32_bf16 v[24:27], v[44:47], v[240:243], v[24:27]
	v_mfma_f32_16x16x32_bf16 v[12:15], v[36:39], v[248:251], v[12:15]
	v_mfma_f32_16x16x32_bf16 v[8:11], v[44:47], v[248:251], v[8:11]
	s_setprio 0
	s_setprio 1
	v_mfma_f32_16x16x32_bf16 v[68:71], v[162:165], v[220:223], v[68:71]
	v_mfma_f32_16x16x32_bf16 v[64:67], v[178:181], v[220:223], v[64:67]
	v_mfma_f32_16x16x32_bf16 v[52:55], v[162:165], v[228:231], v[52:55]
	v_mfma_f32_16x16x32_bf16 v[48:51], v[178:181], v[228:231], v[48:51]
	v_mfma_f32_16x16x32_bf16 v[20:23], v[162:165], v[236:239], v[20:23]
	v_mfma_f32_16x16x32_bf16 v[16:19], v[178:181], v[236:239], v[16:19]
	v_mfma_f32_16x16x32_bf16 v[4:7], v[162:165], v[244:247], v[4:7]
	v_mfma_f32_16x16x32_bf16 v[0:3], v[178:181], v[244:247], v[0:3]
	v_mfma_f32_16x16x32_bf16 v[68:71], v[174:177], v[224:227], v[68:71]
	v_mfma_f32_16x16x32_bf16 v[64:67], v[182:185], v[224:227], v[64:67]
	v_mfma_f32_16x16x32_bf16 v[52:55], v[174:177], v[232:235], v[52:55]
	v_mfma_f32_16x16x32_bf16 v[48:51], v[182:185], v[232:235], v[48:51]
	v_mfma_f32_16x16x32_bf16 v[20:23], v[174:177], v[240:243], v[20:23]
	v_mfma_f32_16x16x32_bf16 v[16:19], v[182:185], v[240:243], v[16:19]
	v_mfma_f32_16x16x32_bf16 v[4:7], v[174:177], v[248:251], v[4:7]
	v_mfma_f32_16x16x32_bf16 v[0:3], v[182:185], v[248:251], v[0:3]
	s_setprio 0
	s_waitcnt vmcnt(0)
	s_barrier
	s_add_u32 vcc_lo, s30, 0x0
	s_addc_u32 vcc_hi, s31, 0
	s_add_u32 s58, vcc_lo, 0x20000
	s_addc_u32 s59, vcc_hi, 0
	s_add_i32 m0, s37, 0x10000
	s_nop 0
	global_load_lds_dwordx4 v148, vcc
	s_add_i32 m0, s37, 0x11000
	s_nop 0
	global_load_lds_dwordx4 v148, s[58:59]
	s_add_i32 m0, s37, 0x12000
	s_nop 0
	global_load_lds_dwordx4 v144, vcc
	s_add_i32 m0, s37, 0x13000
	s_nop 0
	global_load_lds_dwordx4 v144, s[58:59]
	s_add_u32 vcc_lo, s30, 0x80000
	s_addc_u32 vcc_hi, s31, 0
	s_add_u32 s58, vcc_lo, 0x20000
	s_addc_u32 s59, vcc_hi, 0
	s_add_i32 m0, s37, 0x14000
	s_nop 0
	global_load_lds_dwordx4 v148, vcc
	s_add_i32 m0, s37, 0x15000
	s_nop 0
	global_load_lds_dwordx4 v148, s[58:59]
	s_add_i32 m0, s37, 0x16000
	s_nop 0
	global_load_lds_dwordx4 v144, vcc
	s_add_i32 m0, s37, 0x17000
	s_nop 0
	global_load_lds_dwordx4 v144, s[58:59]
	ds_read_b128 v[32:35], v169 offset:32768
	ds_read_b128 v[36:39], v169 offset:33792
	ds_read_b128 v[40:43], v169 offset:34816
	ds_read_b128 v[44:47], v169 offset:35840
	ds_read_b128 v[162:165], v170 offset:32768
	ds_read_b128 v[174:177], v170 offset:33792
	ds_read_b128 v[178:181], v170 offset:34816
	ds_read_b128 v[182:185], v170 offset:35840
	ds_read_b128 v[186:189], v171 offset:32768
	ds_read_b128 v[190:193], v171 offset:33792
	ds_read_b128 v[194:197], v171 offset:34816
	ds_read_b128 v[198:201], v171 offset:35840
	ds_read_b128 v[202:205], v171 offset:36864
	ds_read_b128 v[206:209], v171 offset:37888
	ds_read_b128 v[210:213], v171 offset:38912
	ds_read_b128 v[214:217], v171 offset:39936
	ds_read_b128 v[220:223], v171 offset:49152
	ds_read_b128 v[224:227], v171 offset:50176
	ds_read_b128 v[228:231], v171 offset:51200
	ds_read_b128 v[232:235], v171 offset:52224
	ds_read_b128 v[236:239], v171 offset:53248
	ds_read_b128 v[240:243], v171 offset:54272
	ds_read_b128 v[244:247], v171 offset:55296
	ds_read_b128 v[248:251], v171 offset:56320
	s_nop 15
	s_nop 15
	s_waitcnt lgkmcnt(0)
	s_barrier
	s_setprio 1
	v_mfma_f32_16x16x32_bf16 v[140:143], v[32:35], v[186:189], v[140:143]
	v_mfma_f32_16x16x32_bf16 v[136:139], v[40:43], v[186:189], v[136:139]
	v_mfma_f32_16x16x32_bf16 v[124:127], v[32:35], v[194:197], v[124:127]
	v_mfma_f32_16x16x32_bf16 v[120:123], v[40:43], v[194:197], v[120:123]
	v_mfma_f32_16x16x32_bf16 v[108:111], v[32:35], v[202:205], v[108:111]
	v_mfma_f32_16x16x32_bf16 v[104:107], v[40:43], v[202:205], v[104:107]
	v_mfma_f32_16x16x32_bf16 v[92:95], v[32:35], v[210:213], v[92:95]
	v_mfma_f32_16x16x32_bf16 v[88:91], v[40:43], v[210:213], v[88:91]
	v_mfma_f32_16x16x32_bf16 v[140:143], v[36:39], v[190:193], v[140:143]
	v_mfma_f32_16x16x32_bf16 v[136:139], v[44:47], v[190:193], v[136:139]
	v_mfma_f32_16x16x32_bf16 v[124:127], v[36:39], v[198:201], v[124:127]
	v_mfma_f32_16x16x32_bf16 v[120:123], v[44:47], v[198:201], v[120:123]
	v_mfma_f32_16x16x32_bf16 v[108:111], v[36:39], v[206:209], v[108:111]
	v_mfma_f32_16x16x32_bf16 v[104:107], v[44:47], v[206:209], v[104:107]
	v_mfma_f32_16x16x32_bf16 v[92:95], v[36:39], v[214:217], v[92:95]
	v_mfma_f32_16x16x32_bf16 v[88:91], v[44:47], v[214:217], v[88:91]
	s_setprio 0
	s_setprio 1
	v_mfma_f32_16x16x32_bf16 v[132:135], v[162:165], v[186:189], v[132:135]
	v_mfma_f32_16x16x32_bf16 v[128:131], v[178:181], v[186:189], v[128:131]
	v_mfma_f32_16x16x32_bf16 v[116:119], v[162:165], v[194:197], v[116:119]
	v_mfma_f32_16x16x32_bf16 v[112:115], v[178:181], v[194:197], v[112:115]
	v_mfma_f32_16x16x32_bf16 v[100:103], v[162:165], v[202:205], v[100:103]
	v_mfma_f32_16x16x32_bf16 v[96:99], v[178:181], v[202:205], v[96:99]
	v_mfma_f32_16x16x32_bf16 v[84:87], v[162:165], v[210:213], v[84:87]
	v_mfma_f32_16x16x32_bf16 v[80:83], v[178:181], v[210:213], v[80:83]
	v_mfma_f32_16x16x32_bf16 v[132:135], v[174:177], v[190:193], v[132:135]
	v_mfma_f32_16x16x32_bf16 v[128:131], v[182:185], v[190:193], v[128:131]
	v_mfma_f32_16x16x32_bf16 v[116:119], v[174:177], v[198:201], v[116:119]
	v_mfma_f32_16x16x32_bf16 v[112:115], v[182:185], v[198:201], v[112:115]
	v_mfma_f32_16x16x32_bf16 v[100:103], v[174:177], v[206:209], v[100:103]
	v_mfma_f32_16x16x32_bf16 v[96:99], v[182:185], v[206:209], v[96:99]
	v_mfma_f32_16x16x32_bf16 v[84:87], v[174:177], v[214:217], v[84:87]
	v_mfma_f32_16x16x32_bf16 v[80:83], v[182:185], v[214:217], v[80:83]
	s_setprio 0
	s_setprio 1
	v_mfma_f32_16x16x32_bf16 v[76:79], v[32:35], v[220:223], v[76:79]
	v_mfma_f32_16x16x32_bf16 v[72:75], v[40:43], v[220:223], v[72:75]
	v_mfma_f32_16x16x32_bf16 v[60:63], v[32:35], v[228:231], v[60:63]
	v_mfma_f32_16x16x32_bf16 v[56:59], v[40:43], v[228:231], v[56:59]
	v_mfma_f32_16x16x32_bf16 v[28:31], v[32:35], v[236:239], v[28:31]
	v_mfma_f32_16x16x32_bf16 v[24:27], v[40:43], v[236:239], v[24:27]
	v_mfma_f32_16x16x32_bf16 v[12:15], v[32:35], v[244:247], v[12:15]
	v_mfma_f32_16x16x32_bf16 v[8:11], v[40:43], v[244:247], v[8:11]
	v_mfma_f32_16x16x32_bf16 v[76:79], v[36:39], v[224:227], v[76:79]
	v_mfma_f32_16x16x32_bf16 v[72:75], v[44:47], v[224:227], v[72:75]
	v_mfma_f32_16x16x32_bf16 v[60:63], v[36:39], v[232:235], v[60:63]
	v_mfma_f32_16x16x32_bf16 v[56:59], v[44:47], v[232:235], v[56:59]
	v_mfma_f32_16x16x32_bf16 v[28:31], v[36:39], v[240:243], v[28:31]
	v_mfma_f32_16x16x32_bf16 v[24:27], v[44:47], v[240:243], v[24:27]
	v_mfma_f32_16x16x32_bf16 v[12:15], v[36:39], v[248:251], v[12:15]
	v_mfma_f32_16x16x32_bf16 v[8:11], v[44:47], v[248:251], v[8:11]
	s_setprio 0
	s_setprio 1
	v_mfma_f32_16x16x32_bf16 v[68:71], v[162:165], v[220:223], v[68:71]
	v_mfma_f32_16x16x32_bf16 v[64:67], v[178:181], v[220:223], v[64:67]
	v_mfma_f32_16x16x32_bf16 v[52:55], v[162:165], v[228:231], v[52:55]
	v_mfma_f32_16x16x32_bf16 v[48:51], v[178:181], v[228:231], v[48:51]
	v_mfma_f32_16x16x32_bf16 v[20:23], v[162:165], v[236:239], v[20:23]
	v_mfma_f32_16x16x32_bf16 v[16:19], v[178:181], v[236:239], v[16:19]
	v_mfma_f32_16x16x32_bf16 v[4:7], v[162:165], v[244:247], v[4:7]
	v_mfma_f32_16x16x32_bf16 v[0:3], v[178:181], v[244:247], v[0:3]
	v_mfma_f32_16x16x32_bf16 v[68:71], v[174:177], v[224:227], v[68:71]
	v_mfma_f32_16x16x32_bf16 v[64:67], v[182:185], v[224:227], v[64:67]
	v_mfma_f32_16x16x32_bf16 v[52:55], v[174:177], v[232:235], v[52:55]
	v_mfma_f32_16x16x32_bf16 v[48:51], v[182:185], v[232:235], v[48:51]
	v_mfma_f32_16x16x32_bf16 v[20:23], v[174:177], v[240:243], v[20:23]
	v_mfma_f32_16x16x32_bf16 v[16:19], v[182:185], v[240:243], v[16:19]
	v_mfma_f32_16x16x32_bf16 v[4:7], v[174:177], v[248:251], v[4:7]
	v_mfma_f32_16x16x32_bf16 v[0:3], v[182:185], v[248:251], v[0:3]
	s_setprio 0
	s_waitcnt vmcnt(0)
	s_barrier
	s_add_i32 s56, s56, 2
	s_add_u32 s12, s12, 0x100
	s_addc_u32 s13, s13, 0
	s_add_u32 s54, s54, 0x100
	s_addc_u32 s55, s55, 0
	s_cmp_gt_u32 s56, 29
	s_cbranch_scc0 .LBB0_846
	s_branch .Lk64_done_p6
.Lk64_trail_p6:
	s_sub_u32 vcc_lo, s12, 0x80000
	s_subb_u32 vcc_hi, s13, 0
	s_add_u32 s58, vcc_lo, 0x20000
	s_addc_u32 s59, vcc_hi, 0
	s_add_i32 m0, s37, 0x9000
	s_nop 0
	global_load_lds_dwordx4 v150, s[58:59]
	s_add_i32 m0, s37, 0xa000
	s_nop 0
	global_load_lds_dwordx4 v146, vcc
	s_add_u32 vcc_lo, s12, 0x0
	s_addc_u32 vcc_hi, s13, 0
	s_add_u32 s58, vcc_lo, 0x20000
	s_addc_u32 s59, vcc_hi, 0
	s_add_i32 m0, s37, 0xd000
	s_nop 0
	global_load_lds_dwordx4 v150, s[58:59]
	s_add_i32 m0, s37, 0xe000
	s_nop 0
	global_load_lds_dwordx4 v146, vcc
	s_add_u32 vcc_lo, s34, 0x0
	s_addc_u32 vcc_hi, s35, 0
	s_sub_u32 s58, vcc_lo, 0x20000
	s_subb_u32 s59, vcc_hi, 0
	s_sub_i32 m0, s37, 0x1000
	s_nop 0
	global_load_lds_dwordx4 v150, s[58:59]
	s_mov_b32 m0, s37
	s_nop 0
	global_load_lds_dwordx4 v150, vcc
	s_add_u32 vcc_lo, s34, 0x80000
	s_addc_u32 vcc_hi, s35, 0
	s_sub_u32 s58, vcc_lo, 0x20000
	s_subb_u32 s59, vcc_hi, 0
	s_add_i32 m0, s37, 0x3000
	s_nop 0
	global_load_lds_dwordx4 v150, s[58:59]
	s_add_i32 m0, s37, 0x4000
	s_nop 0
	global_load_lds_dwordx4 v150, vcc
	ds_read_b128 v[32:35], v169 offset:0
	ds_read_b128 v[36:39], v169 offset:1024
	ds_read_b128 v[40:43], v169 offset:2048
	ds_read_b128 v[44:47], v169 offset:3072
	ds_read_b128 v[162:165], v170 offset:0
	ds_read_b128 v[174:177], v170 offset:1024
	ds_read_b128 v[178:181], v170 offset:2048
	ds_read_b128 v[182:185], v170 offset:3072
	ds_read_b128 v[186:189], v171 offset:0
	ds_read_b128 v[190:193], v171 offset:1024
	ds_read_b128 v[194:197], v171 offset:2048
	ds_read_b128 v[198:201], v171 offset:3072
	ds_read_b128 v[202:205], v171 offset:4096
	ds_read_b128 v[206:209], v171 offset:5120
	ds_read_b128 v[210:213], v171 offset:6144
	ds_read_b128 v[214:217], v171 offset:7168
	ds_read_b128 v[220:223], v171 offset:16384
	ds_read_b128 v[224:227], v171 offset:17408
	ds_read_b128 v[228:231], v171 offset:18432
	ds_read_b128 v[232:235], v171 offset:19456
	ds_read_b128 v[236:239], v171 offset:20480
	ds_read_b128 v[240:243], v171 offset:21504
	ds_read_b128 v[244:247], v171 offset:22528
	ds_read_b128 v[248:251], v171 offset:23552
	s_nop 15
	s_nop 15
	s_waitcnt lgkmcnt(0)
	s_barrier
	s_setprio 1
	v_mfma_f32_16x16x32_bf16 v[140:143], v[32:35], v[186:189], v[140:143]
	v_mfma_f32_16x16x32_bf16 v[136:139], v[40:43], v[186:189], v[136:139]
	v_mfma_f32_16x16x32_bf16 v[124:127], v[32:35], v[194:197], v[124:127]
	v_mfma_f32_16x16x32_bf16 v[120:123], v[40:43], v[194:197], v[120:123]
	v_mfma_f32_16x16x32_bf16 v[108:111], v[32:35], v[202:205], v[108:111]
	v_mfma_f32_16x16x32_bf16 v[104:107], v[40:43], v[202:205], v[104:107]
	v_mfma_f32_16x16x32_bf16 v[92:95], v[32:35], v[210:213], v[92:95]
	v_mfma_f32_16x16x32_bf16 v[88:91], v[40:43], v[210:213], v[88:91]
	v_mfma_f32_16x16x32_bf16 v[140:143], v[36:39], v[190:193], v[140:143]
	v_mfma_f32_16x16x32_bf16 v[136:139], v[44:47], v[190:193], v[136:139]
	v_mfma_f32_16x16x32_bf16 v[124:127], v[36:39], v[198:201], v[124:127]
	v_mfma_f32_16x16x32_bf16 v[120:123], v[44:47], v[198:201], v[120:123]
	v_mfma_f32_16x16x32_bf16 v[108:111], v[36:39], v[206:209], v[108:111]
	v_mfma_f32_16x16x32_bf16 v[104:107], v[44:47], v[206:209], v[104:107]
	v_mfma_f32_16x16x32_bf16 v[92:95], v[36:39], v[214:217], v[92:95]
	v_mfma_f32_16x16x32_bf16 v[88:91], v[44:47], v[214:217], v[88:91]
	s_setprio 0
	s_setprio 1
	v_mfma_f32_16x16x32_bf16 v[132:135], v[162:165], v[186:189], v[132:135]
	v_mfma_f32_16x16x32_bf16 v[128:131], v[178:181], v[186:189], v[128:131]
	v_mfma_f32_16x16x32_bf16 v[116:119], v[162:165], v[194:197], v[116:119]
	v_mfma_f32_16x16x32_bf16 v[112:115], v[178:181], v[194:197], v[112:115]
	v_mfma_f32_16x16x32_bf16 v[100:103], v[162:165], v[202:205], v[100:103]
	v_mfma_f32_16x16x32_bf16 v[96:99], v[178:181], v[202:205], v[96:99]
	v_mfma_f32_16x16x32_bf16 v[84:87], v[162:165], v[210:213], v[84:87]
	v_mfma_f32_16x16x32_bf16 v[80:83], v[178:181], v[210:213], v[80:83]
	v_mfma_f32_16x16x32_bf16 v[132:135], v[174:177], v[190:193], v[132:135]
	v_mfma_f32_16x16x32_bf16 v[128:131], v[182:185], v[190:193], v[128:131]
	v_mfma_f32_16x16x32_bf16 v[116:119], v[174:177], v[198:201], v[116:119]
	v_mfma_f32_16x16x32_bf16 v[112:115], v[182:185], v[198:201], v[112:115]
	v_mfma_f32_16x16x32_bf16 v[100:103], v[174:177], v[206:209], v[100:103]
	v_mfma_f32_16x16x32_bf16 v[96:99], v[182:185], v[206:209], v[96:99]
	v_mfma_f32_16x16x32_bf16 v[84:87], v[174:177], v[214:217], v[84:87]
	v_mfma_f32_16x16x32_bf16 v[80:83], v[182:185], v[214:217], v[80:83]
	s_setprio 0
	s_setprio 1
	v_mfma_f32_16x16x32_bf16 v[76:79], v[32:35], v[220:223], v[76:79]
	v_mfma_f32_16x16x32_bf16 v[72:75], v[40:43], v[220:223], v[72:75]
	v_mfma_f32_16x16x32_bf16 v[60:63], v[32:35], v[228:231], v[60:63]
	v_mfma_f32_16x16x32_bf16 v[56:59], v[40:43], v[228:231], v[56:59]
	v_mfma_f32_16x16x32_bf16 v[28:31], v[32:35], v[236:239], v[28:31]
	v_mfma_f32_16x16x32_bf16 v[24:27], v[40:43], v[236:239], v[24:27]
	v_mfma_f32_16x16x32_bf16 v[12:15], v[32:35], v[244:247], v[12:15]
	v_mfma_f32_16x16x32_bf16 v[8:11], v[40:43], v[244:247], v[8:11]
	v_mfma_f32_16x16x32_bf16 v[76:79], v[36:39], v[224:227], v[76:79]
	v_mfma_f32_16x16x32_bf16 v[72:75], v[44:47], v[224:227], v[72:75]
	v_mfma_f32_16x16x32_bf16 v[60:63], v[36:39], v[232:235], v[60:63]
	v_mfma_f32_16x16x32_bf16 v[56:59], v[44:47], v[232:235], v[56:59]
	v_mfma_f32_16x16x32_bf16 v[28:31], v[36:39], v[240:243], v[28:31]
	v_mfma_f32_16x16x32_bf16 v[24:27], v[44:47], v[240:243], v[24:27]
	v_mfma_f32_16x16x32_bf16 v[12:15], v[36:39], v[248:251], v[12:15]
	v_mfma_f32_16x16x32_bf16 v[8:11], v[44:47], v[248:251], v[8:11]
	s_setprio 0
	s_setprio 1
	v_mfma_f32_16x16x32_bf16 v[68:71], v[162:165], v[220:223], v[68:71]
	v_mfma_f32_16x16x32_bf16 v[64:67], v[178:181], v[220:223], v[64:67]
	v_mfma_f32_16x16x32_bf16 v[52:55], v[162:165], v[228:231], v[52:55]
	v_mfma_f32_16x16x32_bf16 v[48:51], v[178:181], v[228:231], v[48:51]
	v_mfma_f32_16x16x32_bf16 v[20:23], v[162:165], v[236:239], v[20:23]
	v_mfma_f32_16x16x32_bf16 v[16:19], v[178:181], v[236:239], v[16:19]
	v_mfma_f32_16x16x32_bf16 v[4:7], v[162:165], v[244:247], v[4:7]
	v_mfma_f32_16x16x32_bf16 v[0:3], v[178:181], v[244:247], v[0:3]
	v_mfma_f32_16x16x32_bf16 v[68:71], v[174:177], v[224:227], v[68:71]
	v_mfma_f32_16x16x32_bf16 v[64:67], v[182:185], v[224:227], v[64:67]
	v_mfma_f32_16x16x32_bf16 v[52:55], v[174:177], v[232:235], v[52:55]
	v_mfma_f32_16x16x32_bf16 v[48:51], v[182:185], v[232:235], v[48:51]
	v_mfma_f32_16x16x32_bf16 v[20:23], v[174:177], v[240:243], v[20:23]
	v_mfma_f32_16x16x32_bf16 v[16:19], v[182:185], v[240:243], v[16:19]
	v_mfma_f32_16x16x32_bf16 v[4:7], v[174:177], v[248:251], v[4:7]
	v_mfma_f32_16x16x32_bf16 v[0:3], v[182:185], v[248:251], v[0:3]
	s_setprio 0
	s_waitcnt vmcnt(0)
	s_barrier
	s_add_u32 vcc_lo, s34, 0x0
	s_addc_u32 vcc_hi, s35, 0
	s_add_u32 s58, vcc_lo, 0x20000
	s_addc_u32 s59, vcc_hi, 0
	s_add_i32 m0, s37, 0x1000
	s_nop 0
	global_load_lds_dwordx4 v150, s[58:59]
	s_add_i32 m0, s37, 0x2000
	s_nop 0
	global_load_lds_dwordx4 v146, vcc
	s_add_u32 vcc_lo, s34, 0x80000
	s_addc_u32 vcc_hi, s35, 0
	s_add_u32 s58, vcc_lo, 0x20000
	s_addc_u32 s59, vcc_hi, 0
	s_add_i32 m0, s37, 0x5000
	s_nop 0
	global_load_lds_dwordx4 v150, s[58:59]
	s_add_i32 m0, s37, 0x6000
	s_nop 0
	global_load_lds_dwordx4 v146, vcc
	s_add_u32 vcc_lo, s34, 0x80
	s_addc_u32 vcc_hi, s35, 0
	s_sub_u32 s58, vcc_lo, 0x20000
	s_subb_u32 s59, vcc_hi, 0
	s_add_i32 m0, s37, 0x7000
	s_nop 0
	global_load_lds_dwordx4 v150, s[58:59]
	s_add_i32 m0, s37, 0x8000
	s_nop 0
	global_load_lds_dwordx4 v150, vcc
	s_add_u32 vcc_lo, s34, 0x80080
	s_addc_u32 vcc_hi, s35, 0
	s_sub_u32 s58, vcc_lo, 0x20000
	s_subb_u32 s59, vcc_hi, 0
	s_add_i32 m0, s37, 0xb000
	s_nop 0
	global_load_lds_dwordx4 v150, s[58:59]
	s_add_i32 m0, s37, 0xc000
	s_nop 0
	global_load_lds_dwordx4 v150, vcc
	ds_read_b128 v[32:35], v169 offset:32768
	ds_read_b128 v[36:39], v169 offset:33792
	ds_read_b128 v[40:43], v169 offset:34816
	ds_read_b128 v[44:47], v169 offset:35840
	ds_read_b128 v[162:165], v170 offset:32768
	ds_read_b128 v[174:177], v170 offset:33792
	ds_read_b128 v[178:181], v170 offset:34816
	ds_read_b128 v[182:185], v170 offset:35840
	ds_read_b128 v[186:189], v171 offset:32768
	ds_read_b128 v[190:193], v171 offset:33792
	ds_read_b128 v[194:197], v171 offset:34816
	ds_read_b128 v[198:201], v171 offset:35840
	ds_read_b128 v[202:205], v171 offset:36864
	ds_read_b128 v[206:209], v171 offset:37888
	ds_read_b128 v[210:213], v171 offset:38912
	ds_read_b128 v[214:217], v171 offset:39936
	ds_read_b128 v[220:223], v171 offset:49152
	ds_read_b128 v[224:227], v171 offset:50176
	ds_read_b128 v[228:231], v171 offset:51200
	ds_read_b128 v[232:235], v171 offset:52224
	ds_read_b128 v[236:239], v171 offset:53248
	ds_read_b128 v[240:243], v171 offset:54272
	ds_read_b128 v[244:247], v171 offset:55296
	ds_read_b128 v[248:251], v171 offset:56320
	s_nop 15
	s_nop 15
	s_waitcnt lgkmcnt(0)
	s_barrier
	s_setprio 1
	v_mfma_f32_16x16x32_bf16 v[140:143], v[32:35], v[186:189], v[140:143]
	v_mfma_f32_16x16x32_bf16 v[136:139], v[40:43], v[186:189], v[136:139]
	v_mfma_f32_16x16x32_bf16 v[124:127], v[32:35], v[194:197], v[124:127]
	v_mfma_f32_16x16x32_bf16 v[120:123], v[40:43], v[194:197], v[120:123]
	v_mfma_f32_16x16x32_bf16 v[108:111], v[32:35], v[202:205], v[108:111]
	v_mfma_f32_16x16x32_bf16 v[104:107], v[40:43], v[202:205], v[104:107]
	v_mfma_f32_16x16x32_bf16 v[92:95], v[32:35], v[210:213], v[92:95]
	v_mfma_f32_16x16x32_bf16 v[88:91], v[40:43], v[210:213], v[88:91]
	v_mfma_f32_16x16x32_bf16 v[140:143], v[36:39], v[190:193], v[140:143]
	v_mfma_f32_16x16x32_bf16 v[136:139], v[44:47], v[190:193], v[136:139]
	v_mfma_f32_16x16x32_bf16 v[124:127], v[36:39], v[198:201], v[124:127]
	v_mfma_f32_16x16x32_bf16 v[120:123], v[44:47], v[198:201], v[120:123]
	v_mfma_f32_16x16x32_bf16 v[108:111], v[36:39], v[206:209], v[108:111]
	v_mfma_f32_16x16x32_bf16 v[104:107], v[44:47], v[206:209], v[104:107]
	v_mfma_f32_16x16x32_bf16 v[92:95], v[36:39], v[214:217], v[92:95]
	v_mfma_f32_16x16x32_bf16 v[88:91], v[44:47], v[214:217], v[88:91]
	s_setprio 0
	s_setprio 1
	v_mfma_f32_16x16x32_bf16 v[132:135], v[162:165], v[186:189], v[132:135]
	v_mfma_f32_16x16x32_bf16 v[128:131], v[178:181], v[186:189], v[128:131]
	v_mfma_f32_16x16x32_bf16 v[116:119], v[162:165], v[194:197], v[116:119]
	v_mfma_f32_16x16x32_bf16 v[112:115], v[178:181], v[194:197], v[112:115]
	v_mfma_f32_16x16x32_bf16 v[100:103], v[162:165], v[202:205], v[100:103]
	v_mfma_f32_16x16x32_bf16 v[96:99], v[178:181], v[202:205], v[96:99]
	v_mfma_f32_16x16x32_bf16 v[84:87], v[162:165], v[210:213], v[84:87]
	v_mfma_f32_16x16x32_bf16 v[80:83], v[178:181], v[210:213], v[80:83]
	v_mfma_f32_16x16x32_bf16 v[132:135], v[174:177], v[190:193], v[132:135]
	v_mfma_f32_16x16x32_bf16 v[128:131], v[182:185], v[190:193], v[128:131]
	v_mfma_f32_16x16x32_bf16 v[116:119], v[174:177], v[198:201], v[116:119]
	v_mfma_f32_16x16x32_bf16 v[112:115], v[182:185], v[198:201], v[112:115]
	v_mfma_f32_16x16x32_bf16 v[100:103], v[174:177], v[206:209], v[100:103]
	v_mfma_f32_16x16x32_bf16 v[96:99], v[182:185], v[206:209], v[96:99]
	v_mfma_f32_16x16x32_bf16 v[84:87], v[174:177], v[214:217], v[84:87]
	v_mfma_f32_16x16x32_bf16 v[80:83], v[182:185], v[214:217], v[80:83]
	s_setprio 0
	s_setprio 1
	v_mfma_f32_16x16x32_bf16 v[76:79], v[32:35], v[220:223], v[76:79]
	v_mfma_f32_16x16x32_bf16 v[72:75], v[40:43], v[220:223], v[72:75]
	v_mfma_f32_16x16x32_bf16 v[60:63], v[32:35], v[228:231], v[60:63]
	v_mfma_f32_16x16x32_bf16 v[56:59], v[40:43], v[228:231], v[56:59]
	v_mfma_f32_16x16x32_bf16 v[28:31], v[32:35], v[236:239], v[28:31]
	v_mfma_f32_16x16x32_bf16 v[24:27], v[40:43], v[236:239], v[24:27]
	v_mfma_f32_16x16x32_bf16 v[12:15], v[32:35], v[244:247], v[12:15]
	v_mfma_f32_16x16x32_bf16 v[8:11], v[40:43], v[244:247], v[8:11]
	v_mfma_f32_16x16x32_bf16 v[76:79], v[36:39], v[224:227], v[76:79]
	v_mfma_f32_16x16x32_bf16 v[72:75], v[44:47], v[224:227], v[72:75]
	v_mfma_f32_16x16x32_bf16 v[60:63], v[36:39], v[232:235], v[60:63]
	v_mfma_f32_16x16x32_bf16 v[56:59], v[44:47], v[232:235], v[56:59]
	v_mfma_f32_16x16x32_bf16 v[28:31], v[36:39], v[240:243], v[28:31]
	v_mfma_f32_16x16x32_bf16 v[24:27], v[44:47], v[240:243], v[24:27]
	v_mfma_f32_16x16x32_bf16 v[12:15], v[36:39], v[248:251], v[12:15]
	v_mfma_f32_16x16x32_bf16 v[8:11], v[44:47], v[248:251], v[8:11]
	s_setprio 0
	s_setprio 1
	v_mfma_f32_16x16x32_bf16 v[68:71], v[162:165], v[220:223], v[68:71]
	v_mfma_f32_16x16x32_bf16 v[64:67], v[178:181], v[220:223], v[64:67]
	v_mfma_f32_16x16x32_bf16 v[52:55], v[162:165], v[228:231], v[52:55]
	v_mfma_f32_16x16x32_bf16 v[48:51], v[178:181], v[228:231], v[48:51]
	v_mfma_f32_16x16x32_bf16 v[20:23], v[162:165], v[236:239], v[20:23]
	v_mfma_f32_16x16x32_bf16 v[16:19], v[178:181], v[236:239], v[16:19]
	v_mfma_f32_16x16x32_bf16 v[4:7], v[162:165], v[244:247], v[4:7]
	v_mfma_f32_16x16x32_bf16 v[0:3], v[178:181], v[244:247], v[0:3]
	v_mfma_f32_16x16x32_bf16 v[68:71], v[174:177], v[224:227], v[68:71]
	v_mfma_f32_16x16x32_bf16 v[64:67], v[182:185], v[224:227], v[64:67]
	v_mfma_f32_16x16x32_bf16 v[52:55], v[174:177], v[232:235], v[52:55]
	v_mfma_f32_16x16x32_bf16 v[48:51], v[182:185], v[232:235], v[48:51]
	v_mfma_f32_16x16x32_bf16 v[20:23], v[174:177], v[240:243], v[20:23]
	v_mfma_f32_16x16x32_bf16 v[16:19], v[182:185], v[240:243], v[16:19]
	v_mfma_f32_16x16x32_bf16 v[4:7], v[174:177], v[248:251], v[4:7]
	v_mfma_f32_16x16x32_bf16 v[0:3], v[182:185], v[248:251], v[0:3]
	s_setprio 0
	s_waitcnt vmcnt(0)
	s_barrier
	s_add_i32 s56, s56, 2
	s_add_u32 s12, s12, 0x100
	s_addc_u32 s13, s13, 0
	s_add_u32 s54, s54, 0x100
	s_addc_u32 s55, s55, 0
	s_cmp_gt_u32 s56, 29
	s_cbranch_scc0 .LBB0_846
.Lk64_done_p6:
	s_and_b64 vcc, exec, s[16:17]
	s_cbranch_vccz .LBB0_849
	s_barrier
.LBB0_849:
	v_lshl_add_u32 v162, s10, 8, v166
	s_ashr_i32 s10, s10, 3
	s_mul_hi_i32 s13, s10, 0xb000
	s_mul_i32 s10, s10, 0xb000
	v_lshl_or_b32 v32, s11, 8, v168
	s_add_u32 s12, s66, s10
	s_addc_u32 s13, s67, s13
	v_ashrrev_i32_e32 v33, 31, v32
	v_ashrrev_i32_e32 v163, 31, v162
	v_lshl_add_u64 v[40:41], v[32:33], 2, s[12:13]
	v_lshl_add_u64 v[164:165], v[162:163], 2, s[18:19]
	global_load_dwordx4 v[36:39], v[40:41], off offset:16
	global_load_dwordx4 v[44:47], v[40:41], off
	global_load_dwordx4 v[32:35], v[40:41], off offset:528
	s_nop 0
	global_load_dwordx4 v[40:43], v[40:41], off offset:512
	s_lshl_b32 s10, s11, 7
	global_load_dword v163, v[164:165], off
	global_load_dword v178, v[164:165], off offset:64
	global_load_dword v179, v[164:165], off offset:128
	global_load_dword v180, v[164:165], off offset:192
	global_load_dword v181, v[164:165], off offset:512
	global_load_dword v182, v[164:165], off offset:576
	global_load_dword v183, v[164:165], off offset:640
	global_load_dword v184, v[164:165], off offset:704
	s_ashr_i32 s11, s10, 31
	s_lshl_b64 s[10:11], s[10:11], 1
	s_andn2_b64 vcc, exec, s[40:41]
	s_waitcnt vmcnt(0)
	v_fmamk_f32 v163, v163, 0x3a000000, v172
	v_rsq_f32_e32 v174, v163
	s_nop 0
	v_pk_fma_f32 v[140:141], v[140:141], v[174:175], v[44:45] op_sel_hi:[1,0,1]
	s_nop 0
	v_mul_f32_e32 v163, 0xbfb8aa3b, v140
	v_exp_f32_e32 v163, v163
	v_pk_fma_f32 v[142:143], v[142:143], v[174:175], v[46:47] op_sel_hi:[1,0,1]
	v_pk_fma_f32 v[138:139], v[138:139], v[174:175], v[38:39] op_sel_hi:[1,0,1]
	v_pk_fma_f32 v[136:137], v[136:137], v[174:175], v[36:37] op_sel_hi:[1,0,1]
	v_add_f32_e32 v163, 1.0, v163
	v_pk_fma_f32 v[132:133], v[132:133], v[174:175], v[40:41] op_sel_hi:[1,0,1]
	v_pk_fma_f32 v[134:135], v[134:135], v[174:175], v[42:43] op_sel_hi:[1,0,1]
	v_pk_fma_f32 v[128:129], v[128:129], v[174:175], v[32:33] op_sel_hi:[1,0,1]
	v_pk_fma_f32 v[130:131], v[130:131], v[174:175], v[34:35] op_sel_hi:[1,0,1]
	v_rcp_f32_e32 v174, v163
	v_mul_f32_e32 v163, 0xbfb8aa3b, v141
	v_exp_f32_e32 v163, v163
	s_nop 0
	v_add_f32_e32 v163, 1.0, v163
	v_rcp_f32_e32 v175, v163
	v_mul_f32_e32 v163, 0xbfb8aa3b, v142
	v_exp_f32_e32 v163, v163
	v_pk_mul_f32 v[140:141], v[140:141], v[174:175]
	s_nop 0
	v_pk_mul_f32 v[132:133], v[132:133], v[140:141]
	v_add_f32_e32 v163, 1.0, v163
	v_rcp_f32_e32 v176, v163
	v_mul_f32_e32 v163, 0xbfb8aa3b, v143
	v_exp_f32_e32 v163, v163
	v_mul_f32_e32 v140, 0xbfb8aa3b, v136
	v_mul_f32_e32 v141, 0xbfb8aa3b, v137
	v_exp_f32_e32 v140, v140
	v_add_f32_e32 v163, 1.0, v163
	v_rcp_f32_e32 v177, v163
	v_exp_f32_e32 v141, v141
	v_add_f32_e32 v140, 1.0, v140
	v_rcp_f32_e32 v140, v140
	v_pk_mul_f32 v[142:143], v[142:143], v[176:177]
	v_add_f32_e32 v141, 1.0, v141
	v_pk_mul_f32 v[134:135], v[134:135], v[142:143]
	v_mul_f32_e32 v142, 0xbfb8aa3b, v138
	v_mul_f32_e32 v143, 0xbfb8aa3b, v139
	v_exp_f32_e32 v142, v142
	v_exp_f32_e32 v143, v143
	v_rcp_f32_e32 v141, v141
	v_add_f32_e32 v142, 1.0, v142
	v_add_f32_e32 v143, 1.0, v143
	v_rcp_f32_e32 v142, v142
	v_rcp_f32_e32 v143, v143
	v_pk_mul_f32 v[136:137], v[136:137], v[140:141]
	v_pk_mul_f32 v[138:139], v[138:139], v[142:143]
	v_pk_mul_f32 v[128:129], v[128:129], v[136:137]
	v_pk_mul_f32 v[138:139], v[130:131], v[138:139]
	v_cvt_pk_bf16_f32 v130, v132, v133
	v_cvt_pk_bf16_f32 v132, v128, v129
	v_mov_b64_e32 v[128:129], s[8:9]
	v_cvt_pk_bf16_f32 v131, v134, v135
	v_mad_i64_i32 v[134:135], s[12:13], v162, s49, v[128:129]
	v_lshl_add_u64 v[134:135], v[134:135], 0, s[10:11]
	v_lshl_add_u64 v[134:135], v[134:135], 0, s[0:1]
	v_cvt_pk_bf16_f32 v133, v138, v139
	v_lshl_add_u64 v[134:135], v[134:135], 0, v[152:153]
	global_store_dwordx4 v[134:135], v[130:133], off
	s_nop 1
	v_or_b32_e32 v130, 16, v162
	v_ashrrev_i32_e32 v131, 31, v130
	v_lshl_add_u64 v[132:133], v[130:131], 2, s[18:19]
	s_nop 1
	v_fmamk_f32 v131, v178, 0x3a000000, v172
	v_rsq_f32_e32 v132, v131
	s_nop 0
	v_pk_fma_f32 v[124:125], v[124:125], v[132:133], v[44:45] op_sel_hi:[1,0,1]
	s_nop 0
	v_mul_f32_e32 v131, 0xbfb8aa3b, v124
	v_exp_f32_e32 v131, v131
	v_pk_fma_f32 v[126:127], v[126:127], v[132:133], v[46:47] op_sel_hi:[1,0,1]
	v_pk_fma_f32 v[122:123], v[122:123], v[132:133], v[38:39] op_sel_hi:[1,0,1]
	v_pk_fma_f32 v[120:121], v[120:121], v[132:133], v[36:37] op_sel_hi:[1,0,1]
	v_add_f32_e32 v131, 1.0, v131
	v_pk_fma_f32 v[116:117], v[116:117], v[132:133], v[40:41] op_sel_hi:[1,0,1]
	v_pk_fma_f32 v[118:119], v[118:119], v[132:133], v[42:43] op_sel_hi:[1,0,1]
	v_pk_fma_f32 v[112:113], v[112:113], v[132:133], v[32:33] op_sel_hi:[1,0,1]
	v_pk_fma_f32 v[114:115], v[114:115], v[132:133], v[34:35] op_sel_hi:[1,0,1]
	v_rcp_f32_e32 v132, v131
	v_mul_f32_e32 v131, 0xbfb8aa3b, v125
	v_exp_f32_e32 v131, v131
	s_nop 0
	v_add_f32_e32 v131, 1.0, v131
	v_rcp_f32_e32 v133, v131
	v_mul_f32_e32 v131, 0xbfb8aa3b, v126
	v_exp_f32_e32 v131, v131
	v_pk_mul_f32 v[124:125], v[124:125], v[132:133]
	s_nop 0
	v_pk_mul_f32 v[116:117], v[116:117], v[124:125]
	v_add_f32_e32 v131, 1.0, v131
	v_rcp_f32_e32 v134, v131
	v_mul_f32_e32 v131, 0xbfb8aa3b, v127
	v_exp_f32_e32 v131, v131
	v_mul_f32_e32 v124, 0xbfb8aa3b, v120
	v_mul_f32_e32 v125, 0xbfb8aa3b, v121
	v_exp_f32_e32 v124, v124
	v_add_f32_e32 v131, 1.0, v131
	v_rcp_f32_e32 v135, v131
	v_exp_f32_e32 v125, v125
	v_add_f32_e32 v124, 1.0, v124
	v_rcp_f32_e32 v124, v124
	v_pk_mul_f32 v[126:127], v[126:127], v[134:135]
	v_add_f32_e32 v125, 1.0, v125
	v_pk_mul_f32 v[118:119], v[118:119], v[126:127]
	v_mul_f32_e32 v126, 0xbfb8aa3b, v122
	v_mul_f32_e32 v127, 0xbfb8aa3b, v123
	v_exp_f32_e32 v126, v126
	v_exp_f32_e32 v127, v127
	v_rcp_f32_e32 v125, v125
	v_add_f32_e32 v126, 1.0, v126
	v_add_f32_e32 v127, 1.0, v127
	v_rcp_f32_e32 v126, v126
	v_rcp_f32_e32 v127, v127
	v_pk_mul_f32 v[120:121], v[120:121], v[124:125]
	v_pk_mul_f32 v[122:123], v[122:123], v[126:127]
	s_nop 0
	v_pk_mul_f32 v[122:123], v[114:115], v[122:123]
	v_pk_mul_f32 v[114:115], v[112:113], v[120:121]
	v_cvt_pk_bf16_f32 v112, v116, v117
	v_mad_i64_i32 v[116:117], s[12:13], v130, s49, v[128:129]
	v_lshl_add_u64 v[116:117], v[116:117], 0, s[10:11]
	v_lshl_add_u64 v[116:117], v[116:117], 0, s[0:1]
	v_cvt_pk_bf16_f32 v113, v118, v119
	v_cvt_pk_bf16_f32 v114, v114, v115
	v_cvt_pk_bf16_f32 v115, v122, v123
	v_lshl_add_u64 v[116:117], v[116:117], 0, v[152:153]
	global_store_dwordx4 v[116:117], v[112:115], off
	s_nop 1
	v_or_b32_e32 v112, 32, v162
	v_ashrrev_i32_e32 v113, 31, v112
	v_lshl_add_u64 v[114:115], v[112:113], 2, s[18:19]
	s_nop 1
	v_fmamk_f32 v113, v179, 0x3a000000, v172
	v_rsq_f32_e32 v114, v113
	s_nop 0
	v_pk_fma_f32 v[108:109], v[108:109], v[114:115], v[44:45] op_sel_hi:[1,0,1]
	s_nop 0
	v_mul_f32_e32 v113, 0xbfb8aa3b, v108
	v_exp_f32_e32 v113, v113
	v_pk_fma_f32 v[110:111], v[110:111], v[114:115], v[46:47] op_sel_hi:[1,0,1]
	v_pk_fma_f32 v[106:107], v[106:107], v[114:115], v[38:39] op_sel_hi:[1,0,1]
	v_pk_fma_f32 v[104:105], v[104:105], v[114:115], v[36:37] op_sel_hi:[1,0,1]
	v_add_f32_e32 v113, 1.0, v113
	v_pk_fma_f32 v[100:101], v[100:101], v[114:115], v[40:41] op_sel_hi:[1,0,1]
	v_pk_fma_f32 v[102:103], v[102:103], v[114:115], v[42:43] op_sel_hi:[1,0,1]
	v_pk_fma_f32 v[96:97], v[96:97], v[114:115], v[32:33] op_sel_hi:[1,0,1]
	v_pk_fma_f32 v[98:99], v[98:99], v[114:115], v[34:35] op_sel_hi:[1,0,1]
	v_rcp_f32_e32 v114, v113
	v_mul_f32_e32 v113, 0xbfb8aa3b, v109
	v_exp_f32_e32 v113, v113
	s_nop 0
	v_add_f32_e32 v113, 1.0, v113
	v_rcp_f32_e32 v115, v113
	v_mul_f32_e32 v113, 0xbfb8aa3b, v110
	v_exp_f32_e32 v113, v113
	v_pk_mul_f32 v[108:109], v[108:109], v[114:115]
	s_nop 0
	v_pk_mul_f32 v[100:101], v[100:101], v[108:109]
	v_add_f32_e32 v113, 1.0, v113
	v_rcp_f32_e32 v116, v113
	v_mul_f32_e32 v113, 0xbfb8aa3b, v111
	v_exp_f32_e32 v113, v113
	v_mul_f32_e32 v108, 0xbfb8aa3b, v104
	v_mul_f32_e32 v109, 0xbfb8aa3b, v105
	v_exp_f32_e32 v108, v108
	v_add_f32_e32 v113, 1.0, v113
	v_rcp_f32_e32 v117, v113
	v_exp_f32_e32 v109, v109
	v_add_f32_e32 v108, 1.0, v108
	v_rcp_f32_e32 v108, v108
	v_pk_mul_f32 v[110:111], v[110:111], v[116:117]
	v_add_f32_e32 v109, 1.0, v109
	v_pk_mul_f32 v[102:103], v[102:103], v[110:111]
	v_mul_f32_e32 v110, 0xbfb8aa3b, v106
	v_mul_f32_e32 v111, 0xbfb8aa3b, v107
	v_exp_f32_e32 v110, v110
	v_exp_f32_e32 v111, v111
	v_rcp_f32_e32 v109, v109
	v_add_f32_e32 v110, 1.0, v110
	v_add_f32_e32 v111, 1.0, v111
	v_rcp_f32_e32 v110, v110
	v_rcp_f32_e32 v111, v111
	v_pk_mul_f32 v[104:105], v[104:105], v[108:109]
	v_pk_mul_f32 v[106:107], v[106:107], v[110:111]
	s_nop 0
	v_pk_mul_f32 v[106:107], v[98:99], v[106:107]
	v_pk_mul_f32 v[98:99], v[96:97], v[104:105]
	v_cvt_pk_bf16_f32 v96, v100, v101
	v_mad_i64_i32 v[100:101], s[12:13], v112, s49, v[128:129]
	v_lshl_add_u64 v[100:101], v[100:101], 0, s[10:11]
	v_lshl_add_u64 v[100:101], v[100:101], 0, s[0:1]
	v_cvt_pk_bf16_f32 v97, v102, v103
	v_cvt_pk_bf16_f32 v98, v98, v99
	v_cvt_pk_bf16_f32 v99, v106, v107
	v_lshl_add_u64 v[100:101], v[100:101], 0, v[152:153]
	global_store_dwordx4 v[100:101], v[96:99], off
	s_nop 1
	v_or_b32_e32 v96, 48, v162
	v_ashrrev_i32_e32 v97, 31, v96
	v_lshl_add_u64 v[98:99], v[96:97], 2, s[18:19]
	s_nop 1
	v_fmamk_f32 v97, v180, 0x3a000000, v172
	v_rsq_f32_e32 v98, v97
	s_nop 0
	v_pk_fma_f32 v[92:93], v[92:93], v[98:99], v[44:45] op_sel_hi:[1,0,1]
	s_nop 0
	v_mul_f32_e32 v97, 0xbfb8aa3b, v92
	v_exp_f32_e32 v97, v97
	v_pk_fma_f32 v[94:95], v[94:95], v[98:99], v[46:47] op_sel_hi:[1,0,1]
	v_pk_fma_f32 v[90:91], v[90:91], v[98:99], v[38:39] op_sel_hi:[1,0,1]
	v_pk_fma_f32 v[88:89], v[88:89], v[98:99], v[36:37] op_sel_hi:[1,0,1]
	v_add_f32_e32 v97, 1.0, v97
	v_pk_fma_f32 v[84:85], v[84:85], v[98:99], v[40:41] op_sel_hi:[1,0,1]
	v_pk_fma_f32 v[86:87], v[86:87], v[98:99], v[42:43] op_sel_hi:[1,0,1]
	v_pk_fma_f32 v[80:81], v[80:81], v[98:99], v[32:33] op_sel_hi:[1,0,1]
	v_pk_fma_f32 v[82:83], v[82:83], v[98:99], v[34:35] op_sel_hi:[1,0,1]
	v_rcp_f32_e32 v98, v97
	v_mul_f32_e32 v97, 0xbfb8aa3b, v93
	v_exp_f32_e32 v97, v97
	s_nop 0
	v_add_f32_e32 v97, 1.0, v97
	v_rcp_f32_e32 v99, v97
	v_mul_f32_e32 v97, 0xbfb8aa3b, v94
	v_exp_f32_e32 v97, v97
	v_pk_mul_f32 v[92:93], v[92:93], v[98:99]
	s_nop 0
	v_pk_mul_f32 v[84:85], v[84:85], v[92:93]
	v_add_f32_e32 v97, 1.0, v97
	v_rcp_f32_e32 v100, v97
	v_mul_f32_e32 v97, 0xbfb8aa3b, v95
	v_exp_f32_e32 v97, v97
	v_mul_f32_e32 v92, 0xbfb8aa3b, v88
	v_mul_f32_e32 v93, 0xbfb8aa3b, v89
	v_exp_f32_e32 v92, v92
	v_add_f32_e32 v97, 1.0, v97
	v_rcp_f32_e32 v101, v97
	v_exp_f32_e32 v93, v93
	v_add_f32_e32 v92, 1.0, v92
	v_rcp_f32_e32 v92, v92
	v_pk_mul_f32 v[94:95], v[94:95], v[100:101]
	v_add_f32_e32 v93, 1.0, v93
	v_pk_mul_f32 v[86:87], v[86:87], v[94:95]
	v_mul_f32_e32 v94, 0xbfb8aa3b, v90
	v_mul_f32_e32 v95, 0xbfb8aa3b, v91
	v_exp_f32_e32 v94, v94
	v_exp_f32_e32 v95, v95
	v_rcp_f32_e32 v93, v93
	v_add_f32_e32 v94, 1.0, v94
	v_add_f32_e32 v95, 1.0, v95
	v_rcp_f32_e32 v94, v94
	v_rcp_f32_e32 v95, v95
	v_pk_mul_f32 v[88:89], v[88:89], v[92:93]
	v_pk_mul_f32 v[90:91], v[90:91], v[94:95]
	s_nop 0
	v_pk_mul_f32 v[90:91], v[82:83], v[90:91]
	v_pk_mul_f32 v[82:83], v[80:81], v[88:89]
	v_cvt_pk_bf16_f32 v80, v84, v85
	v_mad_i64_i32 v[84:85], s[12:13], v96, s49, v[128:129]
	v_lshl_add_u64 v[84:85], v[84:85], 0, s[10:11]
	v_lshl_add_u64 v[84:85], v[84:85], 0, s[0:1]
	v_cvt_pk_bf16_f32 v81, v86, v87
	v_cvt_pk_bf16_f32 v82, v82, v83
	v_cvt_pk_bf16_f32 v83, v90, v91
	v_lshl_add_u64 v[84:85], v[84:85], 0, v[152:153]
	global_store_dwordx4 v[84:85], v[80:83], off
	s_nop 1
	v_add_u32_e32 v84, 0x80, v162
	v_fmamk_f32 v80, v181, 0x3a000000, v172
	v_rsq_f32_e32 v80, v80
	s_nop 0
	v_pk_fma_f32 v[78:79], v[78:79], v[80:81], v[46:47] op_sel_hi:[1,0,1]
	v_pk_fma_f32 v[76:77], v[76:77], v[80:81], v[44:45] op_sel_hi:[1,0,1]
	v_pk_fma_f32 v[74:75], v[74:75], v[80:81], v[38:39] op_sel_hi:[1,0,1]
	v_pk_fma_f32 v[72:73], v[72:73], v[80:81], v[36:37] op_sel_hi:[1,0,1]
	v_pk_fma_f32 v[68:69], v[68:69], v[80:81], v[40:41] op_sel_hi:[1,0,1]
	v_pk_fma_f32 v[70:71], v[70:71], v[80:81], v[42:43] op_sel_hi:[1,0,1]
	v_pk_fma_f32 v[64:65], v[64:65], v[80:81], v[32:33] op_sel_hi:[1,0,1]
	v_pk_fma_f32 v[66:67], v[66:67], v[80:81], v[34:35] op_sel_hi:[1,0,1]
	v_mul_f32_e32 v80, 0xbfb8aa3b, v76
	v_mul_f32_e32 v81, 0xbfb8aa3b, v77
	v_mul_f32_e32 v82, 0xbfb8aa3b, v78
	v_mul_f32_e32 v83, 0xbfb8aa3b, v79
	v_exp_f32_e32 v80, v80
	v_exp_f32_e32 v81, v81
	v_exp_f32_e32 v82, v82
	v_exp_f32_e32 v83, v83
	v_add_f32_e32 v80, 1.0, v80
	v_add_f32_e32 v81, 1.0, v81
	v_add_f32_e32 v82, 1.0, v82
	v_add_f32_e32 v83, 1.0, v83
	v_rcp_f32_e32 v80, v80
	v_rcp_f32_e32 v81, v81
	v_rcp_f32_e32 v82, v82
	v_rcp_f32_e32 v83, v83
	v_pk_mul_f32 v[76:77], v[76:77], v[80:81]
	s_nop 0
	v_pk_mul_f32 v[68:69], v[68:69], v[76:77]
	v_pk_mul_f32 v[78:79], v[78:79], v[82:83]
	v_mul_f32_e32 v76, 0xbfb8aa3b, v72
	v_pk_mul_f32 v[70:71], v[70:71], v[78:79]
	v_mul_f32_e32 v77, 0xbfb8aa3b, v73
	v_mul_f32_e32 v78, 0xbfb8aa3b, v74
	v_mul_f32_e32 v79, 0xbfb8aa3b, v75
	v_exp_f32_e32 v76, v76
	v_exp_f32_e32 v77, v77
	v_exp_f32_e32 v78, v78
	v_exp_f32_e32 v79, v79
	v_add_f32_e32 v76, 1.0, v76
	v_add_f32_e32 v77, 1.0, v77
	v_add_f32_e32 v78, 1.0, v78
	v_add_f32_e32 v79, 1.0, v79
	v_rcp_f32_e32 v76, v76
	v_rcp_f32_e32 v77, v77
	v_rcp_f32_e32 v78, v78
	v_rcp_f32_e32 v79, v79
	v_pk_mul_f32 v[72:73], v[72:73], v[76:77]
	v_pk_mul_f32 v[74:75], v[74:75], v[78:79]
	s_nop 0
	v_pk_mul_f32 v[74:75], v[66:67], v[74:75]
	v_pk_mul_f32 v[66:67], v[64:65], v[72:73]
	v_cvt_pk_bf16_f32 v64, v68, v69
	v_mad_i64_i32 v[68:69], s[12:13], v84, s49, v[128:129]
	v_lshl_add_u64 v[68:69], v[68:69], 0, s[10:11]
	v_lshl_add_u64 v[68:69], v[68:69], 0, s[0:1]
	v_cvt_pk_bf16_f32 v65, v70, v71
	v_cvt_pk_bf16_f32 v66, v66, v67
	v_cvt_pk_bf16_f32 v67, v74, v75
	v_lshl_add_u64 v[68:69], v[68:69], 0, v[152:153]
	global_store_dwordx4 v[68:69], v[64:67], off
	s_nop 1
	v_add_u32_e32 v68, 0x90, v162
	v_fmamk_f32 v64, v182, 0x3a000000, v172
	v_rsq_f32_e32 v64, v64
	s_nop 0
	v_pk_fma_f32 v[62:63], v[62:63], v[64:65], v[46:47] op_sel_hi:[1,0,1]
	v_pk_fma_f32 v[60:61], v[60:61], v[64:65], v[44:45] op_sel_hi:[1,0,1]
	v_pk_fma_f32 v[58:59], v[58:59], v[64:65], v[38:39] op_sel_hi:[1,0,1]
	v_pk_fma_f32 v[56:57], v[56:57], v[64:65], v[36:37] op_sel_hi:[1,0,1]
	v_pk_fma_f32 v[52:53], v[52:53], v[64:65], v[40:41] op_sel_hi:[1,0,1]
	v_pk_fma_f32 v[54:55], v[54:55], v[64:65], v[42:43] op_sel_hi:[1,0,1]
	v_pk_fma_f32 v[48:49], v[48:49], v[64:65], v[32:33] op_sel_hi:[1,0,1]
	v_pk_fma_f32 v[50:51], v[50:51], v[64:65], v[34:35] op_sel_hi:[1,0,1]
	v_mul_f32_e32 v64, 0xbfb8aa3b, v60
	v_mul_f32_e32 v65, 0xbfb8aa3b, v61
	v_mul_f32_e32 v66, 0xbfb8aa3b, v62
	v_mul_f32_e32 v67, 0xbfb8aa3b, v63
	v_exp_f32_e32 v64, v64
	v_exp_f32_e32 v65, v65
	v_exp_f32_e32 v66, v66
	v_exp_f32_e32 v67, v67
	v_add_f32_e32 v64, 1.0, v64
	v_add_f32_e32 v65, 1.0, v65
	v_add_f32_e32 v66, 1.0, v66
	v_add_f32_e32 v67, 1.0, v67
	v_rcp_f32_e32 v64, v64
	v_rcp_f32_e32 v65, v65
	v_rcp_f32_e32 v66, v66
	v_rcp_f32_e32 v67, v67
	v_pk_mul_f32 v[60:61], v[60:61], v[64:65]
	s_nop 0
	v_pk_mul_f32 v[52:53], v[52:53], v[60:61]
	v_pk_mul_f32 v[62:63], v[62:63], v[66:67]
	v_mul_f32_e32 v60, 0xbfb8aa3b, v56
	v_pk_mul_f32 v[54:55], v[54:55], v[62:63]
	v_mul_f32_e32 v61, 0xbfb8aa3b, v57
	v_mul_f32_e32 v62, 0xbfb8aa3b, v58
	v_mul_f32_e32 v63, 0xbfb8aa3b, v59
	v_exp_f32_e32 v60, v60
	v_exp_f32_e32 v61, v61
	v_exp_f32_e32 v62, v62
	v_exp_f32_e32 v63, v63
	v_add_f32_e32 v60, 1.0, v60
	v_add_f32_e32 v61, 1.0, v61
	v_add_f32_e32 v62, 1.0, v62
	v_add_f32_e32 v63, 1.0, v63
	v_rcp_f32_e32 v60, v60
	v_rcp_f32_e32 v61, v61
	v_rcp_f32_e32 v62, v62
	v_rcp_f32_e32 v63, v63
	v_pk_mul_f32 v[56:57], v[56:57], v[60:61]
	v_pk_mul_f32 v[58:59], v[58:59], v[62:63]
	s_nop 0
	v_pk_mul_f32 v[58:59], v[50:51], v[58:59]
	v_pk_mul_f32 v[50:51], v[48:49], v[56:57]
	v_cvt_pk_bf16_f32 v48, v52, v53
	v_mad_i64_i32 v[52:53], s[12:13], v68, s49, v[128:129]
	v_lshl_add_u64 v[52:53], v[52:53], 0, s[10:11]
	v_lshl_add_u64 v[52:53], v[52:53], 0, s[0:1]
	v_cvt_pk_bf16_f32 v49, v54, v55
	v_cvt_pk_bf16_f32 v50, v50, v51
	v_cvt_pk_bf16_f32 v51, v58, v59
	v_lshl_add_u64 v[52:53], v[52:53], 0, v[152:153]
	global_store_dwordx4 v[52:53], v[48:51], off
	s_nop 1
	v_add_u32_e32 v52, 0xa0, v162
	v_fmamk_f32 v48, v183, 0x3a000000, v172
	v_rsq_f32_e32 v48, v48
	s_nop 0
	v_pk_fma_f32 v[30:31], v[30:31], v[48:49], v[46:47] op_sel_hi:[1,0,1]
	v_pk_fma_f32 v[28:29], v[28:29], v[48:49], v[44:45] op_sel_hi:[1,0,1]
	v_pk_fma_f32 v[26:27], v[26:27], v[48:49], v[38:39] op_sel_hi:[1,0,1]
	v_pk_fma_f32 v[24:25], v[24:25], v[48:49], v[36:37] op_sel_hi:[1,0,1]
	v_pk_fma_f32 v[20:21], v[20:21], v[48:49], v[40:41] op_sel_hi:[1,0,1]
	v_pk_fma_f32 v[22:23], v[22:23], v[48:49], v[42:43] op_sel_hi:[1,0,1]
	v_pk_fma_f32 v[16:17], v[16:17], v[48:49], v[32:33] op_sel_hi:[1,0,1]
	v_pk_fma_f32 v[18:19], v[18:19], v[48:49], v[34:35] op_sel_hi:[1,0,1]
	v_mul_f32_e32 v48, 0xbfb8aa3b, v28
	v_mul_f32_e32 v49, 0xbfb8aa3b, v29
	v_mul_f32_e32 v50, 0xbfb8aa3b, v30
	v_mul_f32_e32 v51, 0xbfb8aa3b, v31
	v_exp_f32_e32 v48, v48
	v_exp_f32_e32 v49, v49
	v_exp_f32_e32 v50, v50
	v_exp_f32_e32 v51, v51
	v_add_f32_e32 v48, 1.0, v48
	v_add_f32_e32 v49, 1.0, v49
	v_add_f32_e32 v50, 1.0, v50
	v_add_f32_e32 v51, 1.0, v51
	v_rcp_f32_e32 v48, v48
	v_rcp_f32_e32 v49, v49
	v_rcp_f32_e32 v50, v50
	v_rcp_f32_e32 v51, v51
	v_pk_mul_f32 v[28:29], v[28:29], v[48:49]
	s_nop 0
	v_pk_mul_f32 v[20:21], v[20:21], v[28:29]
	v_pk_mul_f32 v[30:31], v[30:31], v[50:51]
	v_mul_f32_e32 v28, 0xbfb8aa3b, v24
	v_pk_mul_f32 v[22:23], v[22:23], v[30:31]
	v_mul_f32_e32 v29, 0xbfb8aa3b, v25
	v_mul_f32_e32 v30, 0xbfb8aa3b, v26
	v_mul_f32_e32 v31, 0xbfb8aa3b, v27
	v_exp_f32_e32 v28, v28
	v_exp_f32_e32 v29, v29
	v_exp_f32_e32 v30, v30
	v_exp_f32_e32 v31, v31
	v_add_f32_e32 v28, 1.0, v28
	v_add_f32_e32 v29, 1.0, v29
	v_add_f32_e32 v30, 1.0, v30
	v_add_f32_e32 v31, 1.0, v31
	v_rcp_f32_e32 v28, v28
	v_rcp_f32_e32 v29, v29
	v_rcp_f32_e32 v30, v30
	v_rcp_f32_e32 v31, v31
	v_pk_mul_f32 v[24:25], v[24:25], v[28:29]
	v_pk_mul_f32 v[26:27], v[26:27], v[30:31]
	s_nop 0
	v_pk_mul_f32 v[26:27], v[18:19], v[26:27]
	v_pk_mul_f32 v[18:19], v[16:17], v[24:25]
	v_cvt_pk_bf16_f32 v16, v20, v21
	v_mad_i64_i32 v[20:21], s[12:13], v52, s49, v[128:129]
	v_lshl_add_u64 v[20:21], v[20:21], 0, s[10:11]
	v_lshl_add_u64 v[20:21], v[20:21], 0, s[0:1]
	v_cvt_pk_bf16_f32 v17, v22, v23
	v_cvt_pk_bf16_f32 v18, v18, v19
	v_cvt_pk_bf16_f32 v19, v26, v27
	v_lshl_add_u64 v[20:21], v[20:21], 0, v[152:153]
	global_store_dwordx4 v[20:21], v[16:19], off
	s_nop 1
	v_add_u32_e32 v20, 0xb0, v162
	v_fmamk_f32 v16, v184, 0x3a000000, v172
	v_rsq_f32_e32 v16, v16
	s_nop 0
	v_pk_fma_f32 v[14:15], v[14:15], v[16:17], v[46:47] op_sel_hi:[1,0,1]
	v_pk_fma_f32 v[12:13], v[12:13], v[16:17], v[44:45] op_sel_hi:[1,0,1]
	v_pk_fma_f32 v[10:11], v[10:11], v[16:17], v[38:39] op_sel_hi:[1,0,1]
	v_pk_fma_f32 v[8:9], v[8:9], v[16:17], v[36:37] op_sel_hi:[1,0,1]
	v_pk_fma_f32 v[4:5], v[4:5], v[16:17], v[40:41] op_sel_hi:[1,0,1]
	v_pk_fma_f32 v[6:7], v[6:7], v[16:17], v[42:43] op_sel_hi:[1,0,1]
	v_pk_fma_f32 v[0:1], v[0:1], v[16:17], v[32:33] op_sel_hi:[1,0,1]
	v_pk_fma_f32 v[2:3], v[2:3], v[16:17], v[34:35] op_sel_hi:[1,0,1]
	v_mul_f32_e32 v16, 0xbfb8aa3b, v12
	v_mul_f32_e32 v17, 0xbfb8aa3b, v13
	v_mul_f32_e32 v18, 0xbfb8aa3b, v14
	v_mul_f32_e32 v19, 0xbfb8aa3b, v15
	v_exp_f32_e32 v16, v16
	v_exp_f32_e32 v17, v17
	v_exp_f32_e32 v18, v18
	v_exp_f32_e32 v19, v19
	v_add_f32_e32 v16, 1.0, v16
	v_add_f32_e32 v17, 1.0, v17
	v_add_f32_e32 v18, 1.0, v18
	v_add_f32_e32 v19, 1.0, v19
	v_rcp_f32_e32 v16, v16
	v_rcp_f32_e32 v17, v17
	v_rcp_f32_e32 v18, v18
	v_rcp_f32_e32 v19, v19
	v_pk_mul_f32 v[12:13], v[12:13], v[16:17]
	s_nop 0
	v_pk_mul_f32 v[4:5], v[4:5], v[12:13]
	v_pk_mul_f32 v[14:15], v[14:15], v[18:19]
	v_mul_f32_e32 v12, 0xbfb8aa3b, v8
	v_pk_mul_f32 v[6:7], v[6:7], v[14:15]
	v_mul_f32_e32 v13, 0xbfb8aa3b, v9
	v_mul_f32_e32 v14, 0xbfb8aa3b, v10
	v_mul_f32_e32 v15, 0xbfb8aa3b, v11
	v_exp_f32_e32 v12, v12
	v_exp_f32_e32 v13, v13
	v_exp_f32_e32 v14, v14
	v_exp_f32_e32 v15, v15
	v_add_f32_e32 v12, 1.0, v12
	v_add_f32_e32 v13, 1.0, v13
	v_add_f32_e32 v14, 1.0, v14
	v_add_f32_e32 v15, 1.0, v15
	v_rcp_f32_e32 v12, v12
	v_rcp_f32_e32 v13, v13
	v_rcp_f32_e32 v14, v14
	v_rcp_f32_e32 v15, v15
	v_pk_mul_f32 v[8:9], v[8:9], v[12:13]
	v_pk_mul_f32 v[10:11], v[10:11], v[14:15]
	s_nop 0
	v_pk_mul_f32 v[10:11], v[2:3], v[10:11]
	v_pk_mul_f32 v[2:3], v[0:1], v[8:9]
	v_cvt_pk_bf16_f32 v0, v4, v5
	v_mad_i64_i32 v[4:5], s[12:13], v20, s49, v[128:129]
	v_lshl_add_u64 v[4:5], v[4:5], 0, s[10:11]
	v_lshl_add_u64 v[4:5], v[4:5], 0, s[0:1]
	v_cvt_pk_bf16_f32 v1, v6, v7
	v_cvt_pk_bf16_f32 v2, v2, v3
	v_cvt_pk_bf16_f32 v3, v10, v11
	v_lshl_add_u64 v[4:5], v[4:5], 0, v[152:153]
	s_mov_b64 s[10:11], -1
	global_store_dwordx4 v[4:5], v[0:3], off
	s_cbranch_vccnz .LBB0_842
	s_andn2_b64 vcc, exec, s[4:5]
	s_cbranch_vccnz .LBB0_841
	s_barrier
	s_branch .LBB0_841
